# indexer header staging: query fragments go global->LDS directly (LDS-DMA) instead of through registers and ds_write
# speedup vs baseline: 1.0148x; 1.0030x over previous
; #define GAS __attribute__((address_space(1)))
; __device__ __forceinline__ void indexer_unit(const Args& a, LAS unsigned char* lds, LAS unsigned long long* maskl, int b, int qblk, int wave, int lane) {
;     ...
;     const int fr = lane & 15, fq = lane >> 4, t0 = qblk * 16; const size_t rowb = (size_t)b * SEQ;
;     bf16x8 af[8][2]; float wv[8][4];
; #pragma unroll
;     for (int rt = 0; rt < 8; ++rt) {
;         const GAS bf16* p = z + (rowb + t0 + 2 * rt + (fr >> 3)) * ZW + ZIQ + (fr & 7) * 64 + 8 * fq;
;         af[rt][0] = __builtin_nontemporal_load((const GAS bf16x8*)p); af[rt][1] = __builtin_nontemporal_load((const GAS bf16x8*)(p + 32));
;         const u32x2 w = *(const GAS u32x2*)(z + (rowb + t0 + 2 * rt + (fq >> 1)) * ZW + ZIW + 4 * (fq & 1));
;         wv[rt][0] = bflo(w.x); wv[rt][1] = bfhi(w.x); wv[rt][2] = bflo(w.y); wv[rt][3] = bfhi(w.y);
;     }
;     const int nkt = qblk + 1;
;     bf16x8 nb0, nb1;
;     { const int k0 = wave < nkt ? wave : 0; const GAS bf16* p = ikn + (rowb + 16 * k0 + fr) * 64 + 8 * fq; nb0 = *(const GAS bf16x8*)p; nb1 = *(const GAS bf16x8*)(p + 32); }
;     for (int kt = wave; kt < nkt; kt += 8) {
;         const int key = 16 * kt + fr;
;         const bf16x8 b0 = nb0, b1 = nb1;
;         { const int k2 = kt + 8 < nkt ? kt + 8 : kt; const GAS bf16* p = ikn + (rowb + 16 * k2 + fr) * 64 + 8 * fq; nb0 = *(const GAS bf16x8*)p; nb1 = *(const GAS bf16x8*)(p + 32); }
.LBB0_1082:
	v_readlane_b32 s2, v254, 44
	v_mov_b32_e32 v76, v252
	s_or_b32 s9, s8, s2
	s_lshl_b32 s76, s9, 4
	v_and_b32_e32 v5, 63, v76
	v_readlane_b32 s2, v254, 4
	s_cmp_gt_u32 s2, s9
	v_lshlrev_b32_e32 v84, 6, v5
	s_cbranch_scc1 .Lhs_skip
	v_readlane_b32 s14, v254, 46
	v_readlane_b32 s4, v254, 24
	s_add_i32 s2, s76, s14
	v_bfe_u32 v57, v76, 3, 1
	v_readlane_b32 s5, v254, 25
	v_and_b32_e32 v2, 0x1c0, v84
	s_nop 0
	v_mov_b64_e32 v[46:47], s[4:5]
	s_movk_i32 s10, 0x1e00
	v_lshlrev_b32_e32 v48, 1, v2
	v_mov_b32_e32 v49, v4
	v_lshrrev_b32_e32 v119, 5, v5
	v_and_b32_e32 v74, 48, v5
	v_mov_b32_e32 v75, v4
	s_mov_b64 s[12:13], 0x1900
	s_or_b32 s3, s2, 2
	s_movk_i32 s11, 0x1000
	s_or_b32 s3, s2, 4
	s_or_b32 s3, s2, 6
	s_or_b32 s3, s2, 8
	s_or_b32 s3, s2, 10
	s_or_b32 s3, s2, 12
	v_or_b32_e32 v54, s3, v57
	v_mad_u64_u32 v[54:55], s[4:5], v54, s10, v[46:47]
	v_lshl_add_u64 v[54:55], v[54:55], 0, v[48:49]
	v_lshl_add_u64 v[54:55], v[54:55], 0, v[74:75]
	v_add_co_u32_e32 v56, vcc, s11, v54
	s_mov_b64 s[6:7], vcc
	s_or_b32 s4, s2, 14
	v_and_b32_e32 v77, 15, v76
	v_readlane_b32 s2, v254, 47
	s_nop 1
	v_or_b32_e32 v66, s2, v77
	v_mov_b32_e32 v67, v4
	v_readlane_b32 s2, v254, 26
	v_lshlrev_b64 v[66:67], 7, v[66:67]
	v_readlane_b32 s3, v254, 27
	s_nop 1
	v_lshl_add_u64 v[66:67], s[2:3], 0, v[66:67]
	v_lshl_add_u64 v[70:71], v[66:67], 0, v[74:75]
	v_cmp_lt_i32_e32 vcc, v227, v226
	global_load_dwordx4 v[66:69], v[70:71], off offset:64
	global_load_dwordx4 v[70:73], v[70:71], off
	v_readlane_b32 s98, v254, 24
	v_readlane_b32 s99, v254, 25
	v_readlane_b32 s100, v254, 46
	v_bfe_u32 v86, v252, 3, 1
	v_lshrrev_b32_e32 v87, 5, v5
	v_and_b32_e32 v88, 7, v5
	s_add_i32 s100, s100, s76
	s_add_i32 s100, s100, s85
	v_and_b32_e32 v89, 48, v5
	v_lshl_or_b32 v88, v88, 7, v89
	v_or_b32_e32 v86, s100, v86
	v_or_b32_e32 v87, s100, v87
	s_movk_i32 s101, 0x1900
	s_movk_i32 s100, 0x1d90
	v_mul_u32_u24_e32 v86, 0x1e00, v86
	v_mul_u32_u24_e32 v87, 0x1e00, v87
	v_lshrrev_b32_e32 v89, 1, v5
	v_and_b32_e32 v89, 8, v89
	v_add3_u32 v86, v86, v88, s101
	v_add3_u32 v87, v87, v89, s100
	s_lshl_b32 s100, s85, 10
	s_mov_b32 m0, s100
	s_lshl_b32 s101, s85, 8
	global_load_lds_dwordx4 v86, s[98:99] nt
	s_add_i32 s100, s100, 0x3c0
	s_mov_b32 m0, s100
	v_lshl_add_u32 v89, v5, 3, s101
	global_load_lds_dwordx4 v86, s[98:99] offset:64 nt
	global_load_dwordx2 v[98:99], v87, s[98:99]
	s_waitcnt vmcnt(0)
	ds_write_b64 v89, v[98:99] offset:16384
	s_waitcnt lgkmcnt(0)
	s_barrier
	v_lshlrev_b32_e32 v88, 4, v5
	v_lshlrev_b32_e32 v89, 3, v5
	ds_read_b128 v[0:3], v88 offset:0
	ds_read_b128 v[6:9], v88 offset:1024
	ds_read_b128 v[14:17], v88 offset:2048
	ds_read_b128 v[10:13], v88 offset:3072
	ds_read_b128 v[18:21], v88 offset:4096
	ds_read_b128 v[22:25], v88 offset:5120
	ds_read_b128 v[30:33], v88 offset:6144
	ds_read_b128 v[26:29], v88 offset:7168
	ds_read_b128 v[34:37], v88 offset:8192
	ds_read_b128 v[38:41], v88 offset:9216
	ds_read_b128 v[42:45], v88 offset:10240
	ds_read_b128 v[50:53], v88 offset:11264
	ds_read_b128 v[54:57], v88 offset:12288
	ds_read_b128 v[58:61], v88 offset:13312
	ds_read_b128 v[46:49], v88 offset:14336
	ds_read_b128 v[62:65], v88 offset:15360
	ds_read_b64 v[78:79], v89 offset:16384
	ds_read_b64 v[80:81], v89 offset:16896
	ds_read_b64 v[82:83], v89 offset:17408
	ds_read_b64 v[100:101], v89 offset:17920
	ds_read_b64 v[104:105], v89 offset:18432
	ds_read_b64 v[108:109], v89 offset:18944
	ds_read_b64 v[112:113], v89 offset:19456
	ds_read_b64 v[116:117], v89 offset:19968
	s_waitcnt lgkmcnt(0)
	s_barrier
	s_waitcnt vmcnt(0)
	v_lshlrev_b32_e32 v93, 16, v82
	v_and_b32_e32 v94, 0xffff0000, v82
	v_lshlrev_b32_e32 v95, 16, v83
	v_and_b32_e32 v96, 0xffff0000, v83
	v_lshl_add_u64 v[82:83], s[2:3], 0, v[74:75]
	v_cndmask_b32_e32 v74, v253, v227, vcc
	v_lshlrev_b32_e32 v118, 2, v74
	v_and_b32_e32 v74, 16, v76
	v_cmp_eq_u32_e64 s[6:7], 0, v74
	v_lshlrev_b32_e32 v74, 2, v77
	v_lshl_or_b32 v74, v119, 13, v74
	v_readlane_b32 s2, v254, 36
	v_lshlrev_b32_e32 v85, 16, v78
	v_and_b32_e32 v86, 0xffff0000, v78
	v_lshlrev_b32_e32 v87, 16, v79
	v_and_b32_e32 v88, 0xffff0000, v79
	v_lshlrev_b32_e32 v89, 16, v80
	v_and_b32_e32 v90, 0xffff0000, v80
	v_lshlrev_b32_e32 v91, 16, v81
	v_and_b32_e32 v92, 0xffff0000, v81
	v_lshlrev_b32_e32 v97, 16, v100
	v_and_b32_e32 v98, 0xffff0000, v100
	v_lshlrev_b32_e32 v99, 16, v101
	v_and_b32_e32 v100, 0xffff0000, v101
	v_lshlrev_b32_e32 v101, 16, v104
	v_and_b32_e32 v102, 0xffff0000, v104
	v_lshlrev_b32_e32 v103, 16, v105
	v_and_b32_e32 v104, 0xffff0000, v105
	v_lshlrev_b32_e32 v105, 16, v108
	v_and_b32_e32 v106, 0xffff0000, v108
	v_lshlrev_b32_e32 v107, 16, v109
	v_and_b32_e32 v108, 0xffff0000, v109
	v_add_u32_e32 v119, s2, v74
	v_readlane_b32 s10, v254, 4
	v_lshlrev_b32_e32 v109, 16, v112
	v_and_b32_e32 v110, 0xffff0000, v112
	v_lshlrev_b32_e32 v111, 16, v113
	v_and_b32_e32 v112, 0xffff0000, v113
	v_lshlrev_b32_e32 v113, 16, v116
	v_and_b32_e32 v114, 0xffff0000, v116
	v_lshlrev_b32_e32 v115, 16, v117
	v_and_b32_e32 v116, 0xffff0000, v117
	v_or_b32_e32 v117, s14, v77
	s_branch .LBB0_1085

; #define GAS __attribute__((address_space(1)))
; __device__ __forceinline__ void indexer_unit(const Args& a, LAS unsigned char* lds, LAS unsigned long long* maskl, int b, int qblk, int wave, int lane) {
;     ...
;     for (int rt = 0; rt < 8; ++rt) {
;         const GAS bf16* p = z + (rowb + t0 + 2 * rt + (fr >> 3)) * ZW + ZIQ + (fr & 7) * 64 + 8 * fq;
;         af[rt][0] = __builtin_nontemporal_load((const GAS bf16x8*)p); af[rt][1] = __builtin_nontemporal_load((const GAS bf16x8*)(p + 32));
;         const u32x2 w = *(const GAS u32x2*)(z + (rowb + t0 + 2 * rt + (fq >> 1)) * ZW + ZIW + 4 * (fq & 1));
;         wv[rt][0] = bflo(w.x); wv[rt][1] = bfhi(w.x); wv[rt][2] = bflo(w.y); wv[rt][3] = bfhi(w.y);
;     }
.Lhs_skip:
	v_readlane_b32 s98, v254, 24
	v_readlane_b32 s99, v254, 25
	v_readlane_b32 s100, v254, 46
	v_bfe_u32 v86, v252, 3, 1
	v_lshrrev_b32_e32 v87, 5, v5
	v_and_b32_e32 v88, 7, v5
	s_add_i32 s100, s100, s76
	s_add_i32 s100, s100, s85
	v_and_b32_e32 v89, 48, v5
	v_lshl_or_b32 v88, v88, 7, v89
	v_or_b32_e32 v86, s100, v86
	v_or_b32_e32 v87, s100, v87
	s_movk_i32 s101, 0x1900
	s_movk_i32 s100, 0x1d90
	v_mul_u32_u24_e32 v86, 0x1e00, v86
	v_mul_u32_u24_e32 v87, 0x1e00, v87
	v_lshrrev_b32_e32 v89, 1, v5
	v_and_b32_e32 v89, 8, v89
	v_add3_u32 v86, v86, v88, s101
	v_add3_u32 v87, v87, v89, s100
	s_lshl_b32 s100, s85, 10
	s_mov_b32 m0, s100
	s_lshl_b32 s101, s85, 8
	global_load_lds_dwordx4 v86, s[98:99] nt
	s_add_i32 s100, s100, 0x3c0
	s_mov_b32 m0, s100
	v_lshl_add_u32 v89, v5, 3, s101
	global_load_lds_dwordx4 v86, s[98:99] offset:64 nt
	global_load_dwordx2 v[98:99], v87, s[98:99]
	s_waitcnt vmcnt(0)
	ds_write_b64 v89, v[98:99] offset:16384
	s_waitcnt lgkmcnt(0)
	s_barrier
	s_barrier
